# fused sample attention: 8-deep LDS fragment prefetch in the value-projection stages + counted vmcnt on the next block's latents
# speedup vs baseline: 1.0205x; 1.0019x over previous
; #define LAS __attribute__((address_space(3)))
; #define MFMA32(a, b, c) __builtin_amdgcn_mfma_f32_32x32x16_bf16((a), (b), (c), 0, 0, 0)
; DEVI void sample_attn_fused(int wv, LAS unsigned char* lds, int l, int bh) {
;     ...
;     for (int kb = w; kb < FS_NBLK; kb += 8) {
;         const int nkb = kb + 8; const bool more = nkb < FS_NBLK;
;         const bf16_t* ncp = FS_CP(more ? nkb : kb); const float* nrp = FS_RP(more ? nkb : kb);
;         f32x16 x0, x1;
; #pragma unroll
;         for (int r = 0; r < 16; ++r) { x0[r] = 0.f; x1[r] = 0.f; }
; #pragma unroll
;         for (int ks = 0; ks < 16; ++ks) {
;             const bf16x8 a0 = *(const LAS bf16x8*)(wkl + 2 * FS_KO(ks)), a1 = *(const LAS bf16x8*)(wkl + 32 * FS_PITCH + 2 * FS_KO(ks));
;             x0 = MFMA32(a0, cf[ks], x0); x1 = MFMA32(a1, cf[ks], x1);
;             if ((ks & 3) == 3) __builtin_amdgcn_sched_barrier(0);
;         }
.LBB0_1343:
	ds_read_b128 v[34:37], v178
	ds_read_b128 v[38:41], v178 offset:16
	s_add_i32 s12, s27, 8
	s_cmpk_gt_i32 s27, 0x78
	s_cselect_b64 s[54:55], -1, 0
	s_waitcnt vmcnt(15) lgkmcnt(1)
	v_mfma_f32_32x32x16_bf16 v[66:81], v[34:37], v[158:161], 0
	ds_read_b128 v[34:37], v178 offset:16896
	ds_read_b128 v[42:45], v178 offset:16912
	s_cmpk_lt_i32 s27, 0x79
	s_cselect_b64 s[56:57], -1, 0
	s_and_b64 s[2:3], s[56:57], exec
	s_cselect_b32 s36, s12, s27
	s_cmpk_lt_i32 s36, 0x80
	v_lshl_or_b32 v170, s36, 5, v173
	s_waitcnt lgkmcnt(1)
	v_mfma_f32_32x32x16_bf16 v[50:65], v[34:37], v[158:161], 0
	s_cselect_b64 s[2:3], -1, 0
	v_ashrrev_i32_e32 v171, 31, v170
	s_lshl_b32 vcc_lo, s36, 14
	s_mov_b32 vcc_hi, 0
	v_lshl_add_u64 v[190:191], vcc, 0, v[164:165]
	v_cndmask_b32_e64 v191, v163, v191, s[2:3]
	v_cndmask_b32_e64 v190, v162, v190, s[2:3]
	v_add_co_u32_e32 v192, vcc, 0x2000, v190
	s_nop 1
	v_addc_co_u32_e32 v193, vcc, 0, v191, vcc
	s_waitcnt vmcnt(14)
	v_mfma_f32_32x32x16_bf16 v[66:81], v[38:41], v[154:157], v[66:81]
	ds_read_b128 v[34:37], v178 offset:32
	ds_read_b128 v[38:41], v178 offset:48
	s_waitcnt lgkmcnt(2)
	v_mfma_f32_32x32x16_bf16 v[50:65], v[42:45], v[154:157], v[50:65]
	s_waitcnt lgkmcnt(1)
	s_waitcnt vmcnt(13)
	v_mfma_f32_32x32x16_bf16 v[66:81], v[34:37], v[150:153], v[66:81]
	ds_read_b128 v[34:37], v178 offset:16928
	ds_read_b128 v[42:45], v178 offset:16944
	s_waitcnt lgkmcnt(1)
	v_mfma_f32_32x32x16_bf16 v[50:65], v[34:37], v[150:153], v[50:65]
	s_waitcnt vmcnt(12)
	v_mfma_f32_32x32x16_bf16 v[66:81], v[38:41], v[146:149], v[66:81]
	s_waitcnt lgkmcnt(0)
	v_mfma_f32_32x32x16_bf16 v[50:65], v[42:45], v[146:149], v[50:65]
	ds_read_b128 v[34:37], v178 offset:128
	ds_read_b128 v[38:41], v178 offset:144
	s_waitcnt lgkmcnt(1)
	s_waitcnt vmcnt(11)
	v_mfma_f32_32x32x16_bf16 v[66:81], v[34:37], v[142:145], v[66:81]
	ds_read_b128 v[34:37], v178 offset:17024
	ds_read_b128 v[42:45], v178 offset:17040
	s_waitcnt lgkmcnt(1)
	v_mfma_f32_32x32x16_bf16 v[50:65], v[34:37], v[142:145], v[50:65]
	s_waitcnt vmcnt(10)
	v_mfma_f32_32x32x16_bf16 v[66:81], v[38:41], v[138:141], v[66:81]
	ds_read_b128 v[34:37], v178 offset:160
	ds_read_b128 v[38:41], v178 offset:176
	s_waitcnt lgkmcnt(2)
	v_mfma_f32_32x32x16_bf16 v[50:65], v[42:45], v[138:141], v[50:65]
	s_waitcnt lgkmcnt(1)
	s_waitcnt vmcnt(9)
	v_mfma_f32_32x32x16_bf16 v[66:81], v[34:37], v[134:137], v[66:81]
	ds_read_b128 v[34:37], v178 offset:17056
	ds_read_b128 v[42:45], v178 offset:17072
	s_waitcnt lgkmcnt(1)
	v_mfma_f32_32x32x16_bf16 v[50:65], v[34:37], v[134:137], v[50:65]
	s_waitcnt vmcnt(8)
	v_mfma_f32_32x32x16_bf16 v[66:81], v[38:41], v[130:133], v[66:81]
	s_waitcnt lgkmcnt(0)
	v_mfma_f32_32x32x16_bf16 v[50:65], v[42:45], v[130:133], v[50:65]
	ds_read_b128 v[34:37], v178 offset:256
	ds_read_b128 v[38:41], v178 offset:272
	s_waitcnt lgkmcnt(1)
	s_waitcnt vmcnt(7)
	v_mfma_f32_32x32x16_bf16 v[66:81], v[34:37], v[126:129], v[66:81]
	ds_read_b128 v[34:37], v178 offset:17152
	ds_read_b128 v[42:45], v178 offset:17168
	s_waitcnt lgkmcnt(1)
	v_mfma_f32_32x32x16_bf16 v[50:65], v[34:37], v[126:129], v[50:65]
	s_waitcnt vmcnt(6)
	v_mfma_f32_32x32x16_bf16 v[66:81], v[38:41], v[122:125], v[66:81]
	ds_read_b128 v[34:37], v178 offset:288
	ds_read_b128 v[38:41], v178 offset:304
	s_waitcnt lgkmcnt(2)
	v_mfma_f32_32x32x16_bf16 v[50:65], v[42:45], v[122:125], v[50:65]
	s_waitcnt lgkmcnt(1)
	s_waitcnt vmcnt(5)
	v_mfma_f32_32x32x16_bf16 v[66:81], v[34:37], v[118:121], v[66:81]
	ds_read_b128 v[34:37], v178 offset:17184
	ds_read_b128 v[42:45], v178 offset:17200
	s_waitcnt lgkmcnt(1)
	v_mfma_f32_32x32x16_bf16 v[50:65], v[34:37], v[118:121], v[50:65]
	s_waitcnt vmcnt(4)
	v_mfma_f32_32x32x16_bf16 v[66:81], v[38:41], v[114:117], v[66:81]
	s_waitcnt lgkmcnt(0)
	v_mfma_f32_32x32x16_bf16 v[50:65], v[42:45], v[114:117], v[50:65]
	ds_read_b128 v[34:37], v178 offset:384
	ds_read_b128 v[38:41], v178 offset:400
	s_waitcnt lgkmcnt(1)
	s_waitcnt vmcnt(3)
	v_mfma_f32_32x32x16_bf16 v[66:81], v[34:37], v[110:113], v[66:81]
	ds_read_b128 v[34:37], v178 offset:17280
	ds_read_b128 v[42:45], v178 offset:17296
	s_waitcnt lgkmcnt(1)
	v_mfma_f32_32x32x16_bf16 v[50:65], v[34:37], v[110:113], v[50:65]
	s_waitcnt vmcnt(2)
	v_mfma_f32_32x32x16_bf16 v[66:81], v[38:41], v[106:109], v[66:81]
	ds_read_b128 v[34:37], v178 offset:416
	ds_read_b128 v[38:41], v178 offset:432
	s_waitcnt lgkmcnt(2)
	v_mfma_f32_32x32x16_bf16 v[50:65], v[42:45], v[106:109], v[50:65]
	s_waitcnt lgkmcnt(1)
	s_waitcnt vmcnt(1)
	v_mfma_f32_32x32x16_bf16 v[66:81], v[34:37], v[102:105], v[66:81]
	ds_read_b128 v[34:37], v178 offset:17312
	ds_read_b128 v[42:45], v178 offset:17328
	s_waitcnt lgkmcnt(1)
	v_mfma_f32_32x32x16_bf16 v[50:65], v[34:37], v[102:105], v[50:65]
	s_waitcnt vmcnt(0)
	v_mfma_f32_32x32x16_bf16 v[66:81], v[38:41], v[98:101], v[66:81]
	s_waitcnt lgkmcnt(0)
; DEVI u32x4 pack8(const f32x4 a, const f32x4 b) { u32x4 w; w.x = cvtpk(a[0], a[1]); w.y = cvtpk(a[2], a[3]); w.z = cvtpk(b[0], b[1]); w.w = cvtpk(b[2], b[3]); return w; }
; DEVI float ss4(const f32x4 a) { return (a[0] * a[0] + a[1] * a[1]) + (a[2] * a[2] + a[3] * a[3]); }
; #define MFMA32(a, b, c) __builtin_amdgcn_mfma_f32_32x32x16_bf16((a), (b), (c), 0, 0, 0)
; DEVI void sample_attn_fused(int wv, LAS unsigned char* lds, int l, int bh) {
;     ...
;         float ss = (ss4(kr0) + ss4(kr1)) + (ss4(kr2) + ss4(kr3));
; #pragma unroll
;         for (int r = 0; r < 16; ++r) ss += x0[r] * x0[r] + x1[r] * x1[r];
;         ss += __shfl_xor(ss, 32);
;         const float sk = rsqrtf(ss * (1.f / 96.f) + EPSF);
;         f32x16 p;
; #pragma unroll
;         for (int r = 0; r < 16; ++r) p[r] = 0.f;
;         p = MFMA32(pk_regs(x0, 0, sk), qf[0], p); p = MFMA32(pk_regs(x0, 1, sk), qf[64], p);
;         p = MFMA32(pk_regs(x1, 0, sk), qf[128], p); p = MFMA32(pk_regs(x1, 1, sk), qf[192], p);
;         { const u32x4 k0 = pack8(kr0 * sk, kr1 * sk), k1 = pack8(kr2 * sk, kr3 * sk);
;           p = MFMA32(__builtin_bit_cast(bf16x8, k0), qf[256], p); p = MFMA32(__builtin_bit_cast(bf16x8, k1), qf[320], p); }
;         if (more) { kr0 = *(const f32x4*)nrp; kr1 = *(const f32x4*)(nrp + 4); kr2 = *(const f32x4*)(nrp + 16); kr3 = *(const f32x4*)(nrp + 20); }
	v_mfma_f32_32x32x16_bf16 v[50:65], v[42:45], v[98:101], v[50:65]
	v_mul_f32_e32 v34, v91, v91
	v_mul_f32_e32 v35, v93, v93
	v_fmac_f32_e32 v34, v90, v90
	v_fmac_f32_e32 v35, v92, v92
	v_add_f32_e32 v34, v34, v35
	v_mul_f32_e32 v35, v83, v83
	v_mul_f32_e32 v36, v85, v85
	v_fmac_f32_e32 v35, v82, v82
	v_fmac_f32_e32 v36, v84, v84
	v_add_f32_e32 v35, v35, v36
	v_add_f32_e32 v34, v34, v35
	v_mul_f32_e32 v35, v95, v95
	v_mul_f32_e32 v36, v97, v97
	v_fmac_f32_e32 v35, v94, v94
	v_fmac_f32_e32 v36, v96, v96
	v_add_f32_e32 v35, v35, v36
	v_mul_f32_e32 v36, v87, v87
	v_mul_f32_e32 v37, v89, v89
	v_fmac_f32_e32 v36, v86, v86
	v_fmac_f32_e32 v37, v88, v88
	v_add_f32_e32 v36, v36, v37
	v_add_f32_e32 v35, v35, v36
	v_add_f32_e32 v34, v34, v35
	v_mul_f32_e32 v35, v50, v50
	v_fmac_f32_e32 v35, v66, v66
	v_add_f32_e32 v34, v34, v35
	v_mul_f32_e32 v35, v51, v51
	v_fmac_f32_e32 v35, v67, v67
	v_add_f32_e32 v34, v35, v34
	v_mul_f32_e32 v35, v52, v52
	v_fmac_f32_e32 v35, v68, v68
	v_add_f32_e32 v34, v35, v34
	v_mul_f32_e32 v35, v53, v53
	v_fmac_f32_e32 v35, v69, v69
	v_add_f32_e32 v34, v35, v34
	v_mul_f32_e32 v35, v54, v54
	v_fmac_f32_e32 v35, v70, v70
	v_add_f32_e32 v34, v35, v34
	v_mul_f32_e32 v35, v55, v55
	v_fmac_f32_e32 v35, v71, v71
	v_add_f32_e32 v44, v35, v34
	v_pk_mul_f32 v[34:35], v[56:57], v[56:57]
	v_pk_mul_f32 v[36:37], v[58:59], v[58:59]
	v_pk_fma_f32 v[34:35], v[72:73], v[72:73], v[34:35]
	v_pk_fma_f32 v[36:37], v[74:75], v[74:75], v[36:37]
	v_add_f32_e32 v34, v34, v44
	v_add_f32_e32 v34, v35, v34
	v_pk_mul_f32 v[38:39], v[60:61], v[60:61]
	v_add_f32_e32 v34, v36, v34
	v_pk_fma_f32 v[38:39], v[76:77], v[76:77], v[38:39]
	v_add_f32_e32 v34, v37, v34
	v_pk_mul_f32 v[40:41], v[62:63], v[62:63]
	v_add_f32_e32 v34, v38, v34
	v_pk_fma_f32 v[40:41], v[78:79], v[78:79], v[40:41]
	v_add_f32_e32 v34, v39, v34
	v_pk_mul_f32 v[42:43], v[64:65], v[64:65]
	v_add_f32_e32 v34, v40, v34
	v_pk_fma_f32 v[42:43], v[80:81], v[80:81], v[42:43]
	v_add_f32_e32 v34, v41, v34
	v_add_f32_e32 v34, v42, v34
	v_add_f32_e32 v34, v43, v34
	ds_bpermute_b32 v35, v179, v34
	s_waitcnt lgkmcnt(0)
	v_add_f32_e32 v34, v34, v35
	v_fmamk_f32 v34, v34, 0x3c2aaaab, v233
	v_mul_f32_e32 v35, 0x4b800000, v34
	v_cmp_gt_f32_e32 vcc, s25, v34
	s_nop 1
	v_cndmask_b32_e32 v34, v34, v35, vcc
	v_rsq_f32_e32 v34, v34
	s_nop 0
	v_mul_f32_e32 v35, 0x45800000, v34
	v_cndmask_b32_e32 v182, v34, v35, vcc
	v_pk_mul_f32 v[34:35], v[66:67], v[182:183] op_sel_hi:[1,0]
	v_pk_mul_f32 v[36:37], v[68:69], v[182:183] op_sel_hi:[1,0]
	v_cvt_pk_bf16_f32 v34, v34, v35
	v_cvt_pk_bf16_f32 v35, v36, v37
	v_pk_mul_f32 v[36:37], v[70:71], v[182:183] op_sel_hi:[1,0]
	v_pk_mul_f32 v[38:39], v[72:73], v[182:183] op_sel_hi:[1,0]
	v_cvt_pk_bf16_f32 v36, v36, v37
	v_cvt_pk_bf16_f32 v37, v38, v39
	ds_read_b128 v[38:41], v176
	ds_read_b128 v[66:69], v176 offset:1024
	s_waitcnt lgkmcnt(1)
	v_mfma_f32_32x32x16_bf16 v[34:49], v[34:37], v[38:41], 0
	v_mul_f32_e64 v70, v74, v182
	v_mul_f32_e64 v71, v75, v182
	v_mul_f32_e64 v72, v76, v182
	v_mul_f32_e64 v73, v77, v182
	v_cvt_pk_bf16_f32 v70, v70, v71
	v_cvt_pk_bf16_f32 v71, v72, v73
	v_pk_mul_f32 v[72:73], v[78:79], v[182:183] op_sel_hi:[1,0]
	v_pk_mul_f32 v[74:75], v[80:81], v[182:183] op_sel_hi:[1,0]
	v_cvt_pk_bf16_f32 v72, v72, v73
	v_cvt_pk_bf16_f32 v73, v74, v75
	v_pk_mul_f32 v[50:51], v[50:51], v[182:183] op_sel_hi:[1,0]
	v_pk_mul_f32 v[52:53], v[52:53], v[182:183] op_sel_hi:[1,0]
	s_waitcnt lgkmcnt(0)
	v_mfma_f32_32x32x16_bf16 v[34:49], v[70:73], v[66:69], v[34:49]
	v_cvt_pk_bf16_f32 v50, v50, v51
	v_cvt_pk_bf16_f32 v51, v52, v53
	v_mul_f32_e64 v52, v54, v182
	v_mul_f32_e64 v53, v55, v182
	v_mul_f32_e64 v54, v56, v182
	v_mul_f32_e64 v55, v57, v182
	v_cvt_pk_bf16_f32 v52, v52, v53
	v_cvt_pk_bf16_f32 v53, v54, v55
	ds_read_b128 v[54:57], v176 offset:2048
	ds_read_b128 v[66:69], v176 offset:3072
	s_waitcnt lgkmcnt(1)
	v_mfma_f32_32x32x16_bf16 v[34:49], v[50:53], v[54:57], v[34:49]
	v_mul_f32_e64 v50, v58, v182
	v_mul_f32_e64 v51, v59, v182
	v_mul_f32_e64 v52, v60, v182
	v_mul_f32_e64 v53, v61, v182
	v_cvt_pk_bf16_f32 v50, v50, v51
	v_cvt_pk_bf16_f32 v51, v52, v53
	v_pk_mul_f32 v[52:53], v[62:63], v[182:183] op_sel_hi:[1,0]
	v_pk_mul_f32 v[54:55], v[64:65], v[182:183] op_sel_hi:[1,0]
	v_cvt_pk_bf16_f32 v52, v52, v53
	v_cvt_pk_bf16_f32 v53, v54, v55
	v_pk_mul_f32 v[54:55], v[84:85], v[182:183] op_sel_hi:[1,0]
	v_pk_mul_f32 v[56:57], v[82:83], v[182:183] op_sel_hi:[1,0]
	s_waitcnt lgkmcnt(0)
	v_mfma_f32_32x32x16_bf16 v[34:49], v[50:53], v[66:69], v[34:49]
	v_mul_f32_e64 v52, v92, v182
	v_mul_f32_e64 v53, v93, v182
	v_mul_f32_e64 v50, v90, v182
	v_mul_f32_e64 v51, v91, v182
	ds_read_b128 v[62:65], v176 offset:5120
	v_cvt_pk_bf16_f32 v50, v50, v51
	v_cvt_pk_bf16_f32 v51, v52, v53
	v_cvt_pk_bf16_f32 v52, v56, v57
	v_cvt_pk_bf16_f32 v53, v54, v55
	ds_read_b128 v[54:57], v176 offset:4096
	v_pk_mul_f32 v[60:61], v[96:97], v[182:183] op_sel_hi:[1,0]
	s_waitcnt lgkmcnt(0)
	v_mfma_f32_32x32x16_bf16 v[34:49], v[50:53], v[54:57], v[34:49]
	v_mul_f32_e64 v58, v94, v182
	v_mul_f32_e64 v59, v95, v182
	v_mul_f32_e64 v66, v88, v182
	v_mul_f32_e64 v67, v89, v182
	v_mul_f32_e64 v68, v86, v182
	v_mul_f32_e64 v69, v87, v182
	v_cvt_pk_bf16_f32 v58, v58, v59
	v_cvt_pk_bf16_f32 v59, v60, v61
	v_cvt_pk_bf16_f32 v60, v68, v69
	v_cvt_pk_bf16_f32 v61, v66, v67
	s_and_b64 vcc, exec, s[54:55]
	s_nop 0
	v_mfma_f32_32x32x16_bf16 v[34:49], v[58:61], v[62:65], v[34:49]
	s_cbranch_vccnz .LBB0_1345
	v_lshlrev_b64 v[50:51], 7, v[170:171]
	v_lshl_add_u64 v[50:51], v[168:169], 0, v[50:51]
	v_cndmask_b32_e64 v51, v167, v51, s[2:3]
	v_cndmask_b32_e64 v50, v166, v50, s[2:3]
	global_load_dwordx4 v[82:85], v[50:51], off offset:16
	global_load_dwordx4 v[90:93], v[50:51], off
	global_load_dwordx4 v[86:89], v[50:51], off offset:80
	global_load_dwordx4 v[94:97], v[50:51], off offset:64
; #define LAS __attribute__((address_space(3)))
; #define MFMA32(a, b, c) __builtin_amdgcn_mfma_f32_32x32x16_bf16((a), (b), (c), 0, 0, 0)
; DEVI void sample_attn_fused(int wv, LAS unsigned char* lds, int l, int bh) {
;     ...
;         if (kb == 128) {
; #pragma unroll
;             for (int r = 8; r < 16; ++r) p[r] = -INFINITY;
;         }
;         float mx = p[0];
; #pragma unroll
;         for (int r = 1; r < 16; ++r) mx = fmaxf(mx, p[r]);
;         mx = fmaxf(mx, __shfl_xor(mx, 32));
;         const float mn = fmaxf(m_run, mx), alpha = __builtin_amdgcn_exp2f(m_run - mn);
;         m_run = mn;
;         float rs = 0.f;
; #pragma unroll
;         for (int r = 0; r < 16; ++r) { p[r] = __builtin_amdgcn_exp2f(p[r] - mn); rs += p[r]; }
;         l_run = l_run * alpha + rs;
; #pragma unroll
;         for (int r = 0; r < 16; ++r) { o0[r] *= alpha; o1[r] *= alpha; }
;         const bf16x8 pb0 = pk_regs(p, 0, 1.f), pb1 = pk_regs(p, 1, 1.f);
;         {
;             f32x16 v;
; #pragma unroll
;             for (int r = 0; r < 16; ++r) v[r] = 0.f;
; #pragma unroll
;             for (int ks = 0; ks < 16; ++ks) { v = MFMA32(cf[ks], *(const LAS bf16x8*)(wvl + 2 * FS_KO(ks)), v); if ((ks & 3) == 3) __builtin_amdgcn_sched_barrier(0); }
;             o0 = MFMA32(pk_regs(v, 0, 1.f), pb0, o0); o0 = MFMA32(pk_regs(v, 1, 1.f), pb1, o0);
;         }
;         {
;             f32x16 v;
; #pragma unroll
;             for (int r = 0; r < 16; ++r) v[r] = 0.f;
; #pragma unroll
;             for (int ks = 0; ks < 16; ++ks) {
;                 v = MFMA32(cf[ks], *(const LAS bf16x8*)(wvl + 32 * FS_PITCH + 2 * FS_KO(ks)), v);
;                 if (more) cf[ks] = *(const bf16x8*)(ncp + FS_KO(ks));
;                 if ((ks & 3) == 3) __builtin_amdgcn_sched_barrier(0);
.LBB0_1345:
	ds_read_b128 v[196:199], v178 offset:33792
	ds_read_b128 v[200:203], v178 offset:33808
	ds_read_b128 v[204:207], v178 offset:33824
	ds_read_b128 v[208:211], v178 offset:33840
	ds_read_b128 v[212:215], v178 offset:33920
	ds_read_b128 v[216:219], v178 offset:33936
	ds_read_b128 v[220:223], v178 offset:33952
	ds_read_b128 v[224:227], v178 offset:33968
	s_waitcnt lgkmcnt(7)
	v_mfma_f32_32x32x16_bf16 v[50:65], v[158:161], v[196:199], 0
	ds_read_b128 v[196:199], v178 offset:34048
	s_waitcnt lgkmcnt(7)
	v_mfma_f32_32x32x16_bf16 v[50:65], v[154:157], v[200:203], v[50:65]
	ds_read_b128 v[200:203], v178 offset:34064
	s_cmpk_lg_i32 s27, 0x80
	s_cselect_b64 vcc, -1, 0
	v_cndmask_b32_e32 v182, v246, v48, vcc
	v_cndmask_b32_e32 v48, v246, v49, vcc
	s_waitcnt lgkmcnt(7)
	v_mfma_f32_32x32x16_bf16 v[50:65], v[150:153], v[204:207], v[50:65]
	ds_read_b128 v[204:207], v178 offset:34080
	v_cndmask_b32_e32 v49, v246, v46, vcc
	v_cndmask_b32_e32 v46, v246, v47, vcc
	v_cndmask_b32_e32 v47, v246, v44, vcc
	v_cndmask_b32_e32 v44, v246, v45, vcc
	s_waitcnt lgkmcnt(7)
	v_mfma_f32_32x32x16_bf16 v[50:65], v[146:149], v[208:211], v[50:65]
	ds_read_b128 v[208:211], v178 offset:34096
	v_cndmask_b32_e32 v45, v246, v42, vcc
	v_max_f32_e32 v42, v35, v35
	v_max_f32_e32 v70, v34, v34
	v_max_f32_e32 v42, v70, v42
	s_waitcnt lgkmcnt(7)
	v_mfma_f32_32x32x16_bf16 v[50:65], v[142:145], v[212:215], v[50:65]
	ds_read_b128 v[212:215], v178 offset:34176
	v_max3_f32 v42, v42, v36, v37
	v_max3_f32 v42, v42, v38, v39
	v_cndmask_b32_e32 v43, v246, v43, vcc
	v_max3_f32 v42, v42, v40, v41
	s_waitcnt lgkmcnt(7)
	v_mfma_f32_32x32x16_bf16 v[50:65], v[138:141], v[216:219], v[50:65]
	ds_read_b128 v[216:219], v178 offset:34192
	v_max3_f32 v42, v42, v45, v43
	v_max3_f32 v42, v42, v47, v44
	v_max3_f32 v42, v42, v49, v46
	v_max3_f32 v42, v42, v182, v48
	ds_bpermute_b32 v183, v179, v42
	s_waitcnt lgkmcnt(8)
	v_mfma_f32_32x32x16_bf16 v[50:65], v[134:137], v[220:223], v[50:65]
	ds_read_b128 v[220:223], v178 offset:34208
	s_waitcnt lgkmcnt(8)
	v_mfma_f32_32x32x16_bf16 v[50:65], v[130:133], v[224:227], v[50:65]
	ds_read_b128 v[224:227], v178 offset:34224
	s_waitcnt lgkmcnt(8)
	v_mfma_f32_32x32x16_bf16 v[50:65], v[126:129], v[196:199], v[50:65]
	ds_read_b128 v[196:199], v178 offset:50688
	s_waitcnt lgkmcnt(8)
	v_mfma_f32_32x32x16_bf16 v[50:65], v[122:125], v[200:203], v[50:65]
	ds_read_b128 v[200:203], v178 offset:50704
	s_waitcnt lgkmcnt(8)
	v_mfma_f32_32x32x16_bf16 v[50:65], v[118:121], v[204:207], v[50:65]
	ds_read_b128 v[204:207], v178 offset:50720
	s_waitcnt lgkmcnt(8)
	v_mfma_f32_32x32x16_bf16 v[50:65], v[114:117], v[208:211], v[50:65]
	ds_read_b128 v[208:211], v178 offset:50736
	s_waitcnt lgkmcnt(8)
	v_mfma_f32_32x32x16_bf16 v[50:65], v[110:113], v[212:215], v[50:65]
	ds_read_b128 v[212:215], v178 offset:50816
	s_waitcnt lgkmcnt(8)
	v_mfma_f32_32x32x16_bf16 v[50:65], v[106:109], v[216:219], v[50:65]
	ds_read_b128 v[216:219], v178 offset:50832
	s_waitcnt lgkmcnt(7)
	v_mfma_f32_32x32x16_bf16 v[50:65], v[102:105], v[220:223], v[50:65]
	ds_read_b128 v[220:223], v178 offset:50848
	s_waitcnt lgkmcnt(7)
	v_mfma_f32_32x32x16_bf16 v[50:65], v[98:101], v[224:227], v[50:65]
	ds_read_b128 v[224:227], v178 offset:50864
	s_andn2_b64 vcc, exec, s[56:57]
	s_waitcnt lgkmcnt(7)
	v_mfma_f32_32x32x16_bf16 v[66:81], v[158:161], v[196:199], 0
	s_cbranch_vccnz .Lsa_nl0
	global_load_dwordx4 v[158:161], v[190:191], off offset:-4096
.Lsa_nl0:
	ds_read_b128 v[196:199], v178 offset:50944
	s_waitcnt lgkmcnt(7)
	v_mfma_f32_32x32x16_bf16 v[66:81], v[154:157], v[200:203], v[66:81]
	s_cbranch_vccnz .Lsa_nl1
	global_load_dwordx4 v[154:157], v[190:191], off offset:-3072
.Lsa_nl1:
	ds_read_b128 v[200:203], v178 offset:50960
	s_waitcnt lgkmcnt(7)
	v_mfma_f32_32x32x16_bf16 v[66:81], v[150:153], v[204:207], v[66:81]
	s_cbranch_vccnz .Lsa_nl2
	global_load_dwordx4 v[150:153], v[190:191], off offset:-2048
.Lsa_nl2:
	ds_read_b128 v[204:207], v178 offset:50976
	s_waitcnt lgkmcnt(7)
	v_mfma_f32_32x32x16_bf16 v[66:81], v[146:149], v[208:211], v[66:81]
	s_cbranch_vccnz .Lsa_nl3
	global_load_dwordx4 v[146:149], v[190:191], off offset:-1024
.Lsa_nl3:
	ds_read_b128 v[208:211], v178 offset:50992
	s_waitcnt lgkmcnt(7)
	v_mfma_f32_32x32x16_bf16 v[66:81], v[142:145], v[212:215], v[66:81]
	s_cbranch_vccnz .Lsa_nl4
	global_load_dwordx4 v[142:145], v[190:191], off
.Lsa_nl4:
	ds_read_b128 v[212:215], v178 offset:51072
	s_waitcnt lgkmcnt(7)
	v_mfma_f32_32x32x16_bf16 v[66:81], v[138:141], v[216:219], v[66:81]
	s_cbranch_vccnz .Lsa_nl5
	global_load_dwordx4 v[138:141], v[190:191], off offset:1024
.Lsa_nl5:
	ds_read_b128 v[216:219], v178 offset:51088
	s_waitcnt lgkmcnt(7)
	v_mfma_f32_32x32x16_bf16 v[66:81], v[134:137], v[220:223], v[66:81]
	s_cbranch_vccnz .Lsa_nl6
	global_load_dwordx4 v[134:137], v[190:191], off offset:2048
.Lsa_nl6:
	ds_read_b128 v[220:223], v178 offset:51104
	s_waitcnt lgkmcnt(7)
	v_mfma_f32_32x32x16_bf16 v[66:81], v[130:133], v[224:227], v[66:81]
	s_cbranch_vccnz .Lsa_nl7
	global_load_dwordx4 v[130:133], v[190:191], off offset:3072
; #define LAS __attribute__((address_space(3)))
; #define MFMA32(a, b, c) __builtin_amdgcn_mfma_f32_32x32x16_bf16((a), (b), (c), 0, 0, 0)
; DEVI void sample_attn_fused(int wv, LAS unsigned char* lds, int l, int bh) {
;     ...
;         mx = fmaxf(mx, __shfl_xor(mx, 32));
;         const float mn = fmaxf(m_run, mx), alpha = __builtin_amdgcn_exp2f(m_run - mn);
;         m_run = mn;
;         float rs = 0.f;
; #pragma unroll
;         for (int r = 0; r < 16; ++r) { p[r] = __builtin_amdgcn_exp2f(p[r] - mn); rs += p[r]; }
;         l_run = l_run * alpha + rs;
; #pragma unroll
;         for (int r = 0; r < 16; ++r) { o0[r] *= alpha; o1[r] *= alpha; }
;         const bf16x8 pb0 = pk_regs(p, 0, 1.f), pb1 = pk_regs(p, 1, 1.f);
;         {
;             f32x16 v;
; #pragma unroll
;             for (int r = 0; r < 16; ++r) v[r] = 0.f;
; #pragma unroll
;             for (int ks = 0; ks < 16; ++ks) { v = MFMA32(cf[ks], *(const LAS bf16x8*)(wvl + 2 * FS_KO(ks)), v); if ((ks & 3) == 3) __builtin_amdgcn_sched_barrier(0); }
;             o0 = MFMA32(pk_regs(v, 0, 1.f), pb0, o0); o0 = MFMA32(pk_regs(v, 1, 1.f), pb1, o0);
;         }
;         {
;             f32x16 v;
; #pragma unroll
;             for (int r = 0; r < 16; ++r) v[r] = 0.f;
; #pragma unroll
;             for (int ks = 0; ks < 16; ++ks) {
;                 v = MFMA32(cf[ks], *(const LAS bf16x8*)(wvl + 32 * FS_PITCH + 2 * FS_KO(ks)), v);
;                 if (more) cf[ks] = *(const bf16x8*)(ncp + FS_KO(ks));
;                 if ((ks & 3) == 3) __builtin_amdgcn_sched_barrier(0);
;             }
;             o1 = MFMA32(pk_regs(v, 0, 1.f), pb0, o1); o1 = MFMA32(pk_regs(v, 1, 1.f), pb1, o1);
;         }
.Lsa_nl7:
	ds_read_b128 v[224:227], v178 offset:51120
	s_waitcnt lgkmcnt(7)
	v_mfma_f32_32x32x16_bf16 v[66:81], v[126:129], v[196:199], v[66:81]
	s_cbranch_vccnz .Lsa_nl8
	global_load_dwordx4 v[126:129], v[192:193], off offset:-4096
.Lsa_nl8:
	s_waitcnt lgkmcnt(6)
	v_mfma_f32_32x32x16_bf16 v[66:81], v[122:125], v[200:203], v[66:81]
	s_cbranch_vccnz .Lsa_nl9
	global_load_dwordx4 v[122:125], v[192:193], off offset:-3072
.Lsa_nl9:
	s_waitcnt lgkmcnt(5)
	v_mfma_f32_32x32x16_bf16 v[66:81], v[118:121], v[204:207], v[66:81]
	s_cbranch_vccnz .Lsa_nl10
	global_load_dwordx4 v[118:121], v[192:193], off offset:-2048
.Lsa_nl10:
	s_waitcnt lgkmcnt(4)
	v_mfma_f32_32x32x16_bf16 v[66:81], v[114:117], v[208:211], v[66:81]
	s_cbranch_vccnz .Lsa_nl11
	global_load_dwordx4 v[114:117], v[192:193], off offset:-1024
.Lsa_nl11:
	s_waitcnt lgkmcnt(3)
	v_mfma_f32_32x32x16_bf16 v[66:81], v[110:113], v[212:215], v[66:81]
	s_cbranch_vccnz .Lsa_nl12
	global_load_dwordx4 v[110:113], v[192:193], off
.Lsa_nl12:
	s_waitcnt lgkmcnt(2)
	v_mfma_f32_32x32x16_bf16 v[66:81], v[106:109], v[216:219], v[66:81]
	s_cbranch_vccnz .Lsa_nl13
	global_load_dwordx4 v[106:109], v[192:193], off offset:1024
.Lsa_nl13:
	s_waitcnt lgkmcnt(1)
	v_mfma_f32_32x32x16_bf16 v[66:81], v[102:105], v[220:223], v[66:81]
	s_cbranch_vccnz .Lsa_nl14
	global_load_dwordx4 v[102:105], v[192:193], off offset:2048
.Lsa_nl14:
	s_waitcnt lgkmcnt(0)
	v_mfma_f32_32x32x16_bf16 v[66:81], v[98:101], v[224:227], v[66:81]
	s_cbranch_vccnz .Lsa_nl15
	global_load_dwordx4 v[98:101], v[192:193], off offset:3072
.Lsa_nl15:
.LBB0_1377:
	v_max3_f32 v42, v181, v42, v183
	v_sub_f32_e32 v34, v34, v42
	v_exp_f32_e32 v171, v34
	v_sub_f32_e32 v34, v35, v42
	v_exp_f32_e32 v35, v34
	v_sub_f32_e32 v34, v36, v42
	v_sub_f32_e32 v170, v181, v42
	v_exp_f32_e32 v181, v34
	v_sub_f32_e32 v34, v37, v42
	v_exp_f32_e32 v37, v34
	v_sub_f32_e32 v34, v38, v42
	v_exp_f32_e32 v38, v34
	v_sub_f32_e32 v34, v39, v42
	v_exp_f32_e32 v39, v34
	v_sub_f32_e32 v34, v40, v42
	v_exp_f32_e32 v40, v34
	v_sub_f32_e32 v34, v41, v42
	v_exp_f32_e32 v41, v34
	v_sub_f32_e32 v34, v45, v42
	v_exp_f32_e32 v45, v34
	v_sub_f32_e32 v34, v43, v42
	v_exp_f32_e32 v43, v34
	v_sub_f32_e32 v34, v47, v42
	v_exp_f32_e32 v47, v34
	v_sub_f32_e32 v34, v44, v42
	v_exp_f32_e32 v183, v34
	v_sub_f32_e32 v34, v49, v42
	v_exp_f32_e32 v49, v34
	v_sub_f32_e32 v34, v46, v42
	v_exp_f32_e32 v46, v34
	v_sub_f32_e32 v34, v182, v42
	v_exp_f32_e32 v182, v34
	v_sub_f32_e32 v34, v48, v42
	v_exp_f32_e32 v48, v34
	v_add_f32_e32 v34, 0, v171
	v_add_f32_e32 v34, v35, v34
	v_add_f32_e32 v34, v181, v34
	v_add_f32_e32 v34, v37, v34
	v_add_f32_e32 v34, v38, v34
	v_add_f32_e32 v34, v39, v34
	v_add_f32_e32 v34, v40, v34
	v_add_f32_e32 v34, v41, v34
	v_add_f32_e32 v34, v45, v34
	v_add_f32_e32 v34, v43, v34
	v_add_f32_e32 v34, v47, v34
	v_exp_f32_e32 v170, v170
	v_add_f32_e32 v34, v183, v34
	v_add_f32_e32 v34, v49, v34
	v_add_f32_e32 v34, v46, v34
	v_add_f32_e32 v34, v182, v34
	v_add_f32_e32 v34, v48, v34
	v_pk_mul_f32 v[32:33], v[32:33], v[170:171] op_sel_hi:[1,0]
	v_pk_mul_f32 v[30:31], v[30:31], v[170:171] op_sel_hi:[1,0]
	v_pk_mul_f32 v[28:29], v[28:29], v[170:171] op_sel_hi:[1,0]
	v_pk_mul_f32 v[26:27], v[26:27], v[170:171] op_sel_hi:[1,0]
	v_pk_mul_f32 v[24:25], v[24:25], v[170:171] op_sel_hi:[1,0]
	v_pk_mul_f32 v[22:23], v[22:23], v[170:171] op_sel_hi:[1,0]
	v_pk_mul_f32 v[20:21], v[20:21], v[170:171] op_sel_hi:[1,0]
	v_pk_mul_f32 v[18:19], v[18:19], v[170:171] op_sel_hi:[1,0]
	v_pk_mul_f32 v[16:17], v[16:17], v[170:171] op_sel_hi:[1,0]
	v_pk_mul_f32 v[14:15], v[14:15], v[170:171] op_sel_hi:[1,0]
	v_pk_mul_f32 v[12:13], v[12:13], v[170:171] op_sel_hi:[1,0]
	v_pk_mul_f32 v[10:11], v[10:11], v[170:171] op_sel_hi:[1,0]
	v_pk_mul_f32 v[8:9], v[8:9], v[170:171] op_sel_hi:[1,0]
	v_pk_mul_f32 v[6:7], v[6:7], v[170:171] op_sel_hi:[1,0]
	v_pk_mul_f32 v[4:5], v[4:5], v[170:171] op_sel_hi:[1,0]
	v_pk_mul_f32 v[2:3], v[2:3], v[170:171] op_sel_hi:[1,0]
	v_cvt_pk_bf16_f32 v36, v171, v35
	v_cvt_pk_bf16_f32 v37, v181, v37
	v_cvt_pk_bf16_f32 v38, v38, v39
	v_cvt_pk_bf16_f32 v39, v40, v41
	v_cvt_pk_bf16_f32 v44, v45, v43
	v_cvt_pk_bf16_f32 v45, v47, v183
	v_cvt_pk_bf16_f32 v46, v49, v46
	v_cvt_pk_bf16_f32 v47, v182, v48
	v_cvt_pk_bf16_f32 v48, v50, v51
	v_cvt_pk_bf16_f32 v49, v52, v53
	v_cvt_pk_bf16_f32 v50, v54, v55
	v_cvt_pk_bf16_f32 v51, v56, v57
	v_cvt_pk_bf16_f32 v52, v58, v59
	v_cvt_pk_bf16_f32 v53, v60, v61
	v_cvt_pk_bf16_f32 v54, v62, v63
	v_cvt_pk_bf16_f32 v55, v64, v65
	v_mfma_f32_32x32x16_bf16 v[2:17], v[48:51], v[36:39], v[2:17]
	v_cvt_pk_bf16_f32 v48, v66, v67
	v_cvt_pk_bf16_f32 v49, v68, v69
	v_cvt_pk_bf16_f32 v50, v70, v71
	v_cvt_pk_bf16_f32 v51, v72, v73
	v_fmac_f32_e32 v34, v180, v170
	s_and_b64 vcc, exec, s[54:55]
	v_mfma_f32_32x32x16_bf16 v[18:33], v[48:51], v[36:39], v[18:33]
	v_cvt_pk_bf16_f32 v36, v74, v75
	v_cvt_pk_bf16_f32 v37, v76, v77
	v_cvt_pk_bf16_f32 v38, v78, v79
	v_cvt_pk_bf16_f32 v39, v80, v81
	v_mfma_f32_32x32x16_bf16 v[2:17], v[52:55], v[44:47], v[2:17]
	s_nop 0
	v_mfma_f32_32x32x16_bf16 v[18:33], v[36:39], v[44:47], v[18:33]
	s_cbranch_vccnz .LBB0_1380
	v_mov_b32_e32 v180, v34
	v_mov_b32_e32 v181, v42
	s_mov_b32 s27, s12
	s_branch .LBB0_1343
